# v40 plus the same SGPR-base DMA address conversion in the Down steady loop
# baseline (speedup 1.0000x reference)
.LBB0_649:
	s_or_b32 s38, s28, 1
	s_lshl_b64 s[42:43], s[38:39], 7
	s_sub_u32 s38, 0, s42
	s_subb_u32 s42, 0, s43
	s_add_u32 s38, s6, s38
	s_addc_u32 s43, s7, s42
	s_add_i32 s71, 0, 0x10000
	s_add_i32 s72, 0, 0x14000
	s_waitcnt lgkmcnt(0)
	ds_read_b128 v[132:135], v240
	ds_read_b128 v[136:139], v240 offset:1024
	ds_read_b128 v[140:143], v240 offset:2048
	ds_read_b128 v[144:147], v240 offset:3072
	ds_read_b128 v[148:151], v240 offset:16384
	ds_read_b128 v[152:155], v240 offset:17408
	ds_read_b128 v[156:159], v240 offset:18432
	ds_read_b128 v[160:163], v240 offset:19456
	s_add_u32 s42, s38, 0x160000
	s_mov_b32 m0, s64
	s_addc_u32 s43, s43, 0
	ds_read_b128 v[164:167], v231
	ds_read_b128 v[168:171], v231 offset:1024
	ds_read_b128 v[172:175], v231 offset:2048
	ds_read_b128 v[176:179], v231 offset:3072
	ds_read_b128 v[180:183], v231 offset:4096
	ds_read_b128 v[184:187], v231 offset:5120
	ds_read_b128 v[194:197], v231 offset:6144
	ds_read_b128 v[198:201], v231 offset:7168
	global_load_lds_dwordx4 v2, s[42:43]
	s_mov_b32 m0, s65
	v_mov_b32_e32 v189, v3
	global_load_lds_dwordx4 v188, s[42:43]
	s_waitcnt vmcnt(8)
	s_waitcnt lgkmcnt(0)
	s_barrier
	s_setprio 1
	s_waitcnt lgkmcnt(0)
	v_mfma_f32_16x16x32_bf16 v[4:7], v[132:135], v[164:167], v[4:7]
	v_mfma_f32_16x16x32_bf16 v[4:7], v[136:139], v[168:171], v[4:7]
	v_mfma_f32_16x16x32_bf16 v[8:11], v[144:147], v[168:171], v[8:11]
	v_mfma_f32_16x16x32_bf16 v[8:11], v[140:143], v[164:167], v[8:11]
	v_mfma_f32_16x16x32_bf16 v[16:19], v[140:143], v[172:175], v[16:19]
	v_mfma_f32_16x16x32_bf16 v[16:19], v[144:147], v[176:179], v[16:19]
	v_mfma_f32_16x16x32_bf16 v[12:15], v[136:139], v[176:179], v[12:15]
	v_mfma_f32_16x16x32_bf16 v[12:15], v[132:135], v[172:175], v[12:15]
	v_mfma_f32_16x16x32_bf16 v[20:23], v[132:135], v[180:183], v[20:23]
	v_mfma_f32_16x16x32_bf16 v[20:23], v[136:139], v[184:187], v[20:23]
	v_mfma_f32_16x16x32_bf16 v[24:27], v[144:147], v[184:187], v[24:27]
	v_mfma_f32_16x16x32_bf16 v[24:27], v[140:143], v[180:183], v[24:27]
	v_mfma_f32_16x16x32_bf16 v[32:35], v[140:143], v[194:197], v[32:35]
	v_mfma_f32_16x16x32_bf16 v[32:35], v[144:147], v[198:201], v[32:35]
	v_mfma_f32_16x16x32_bf16 v[28:31], v[136:139], v[198:201], v[28:31]
	v_mfma_f32_16x16x32_bf16 v[28:31], v[132:135], v[194:197], v[28:31]
	s_setprio 0
	s_setprio 1
	v_mfma_f32_16x16x32_bf16 v[36:39], v[148:151], v[164:167], v[36:39]
	v_mfma_f32_16x16x32_bf16 v[36:39], v[152:155], v[168:171], v[36:39]
	v_mfma_f32_16x16x32_bf16 v[40:43], v[160:163], v[168:171], v[40:43]
	v_mfma_f32_16x16x32_bf16 v[40:43], v[156:159], v[164:167], v[40:43]
	v_mfma_f32_16x16x32_bf16 v[48:51], v[156:159], v[172:175], v[48:51]
	v_mfma_f32_16x16x32_bf16 v[48:51], v[160:163], v[176:179], v[48:51]
	v_mfma_f32_16x16x32_bf16 v[44:47], v[152:155], v[176:179], v[44:47]
	v_mfma_f32_16x16x32_bf16 v[44:47], v[148:151], v[172:175], v[44:47]
	v_mfma_f32_16x16x32_bf16 v[52:55], v[148:151], v[180:183], v[52:55]
	v_mfma_f32_16x16x32_bf16 v[52:55], v[152:155], v[184:187], v[52:55]
	v_mfma_f32_16x16x32_bf16 v[56:59], v[160:163], v[184:187], v[56:59]
	v_mfma_f32_16x16x32_bf16 v[56:59], v[156:159], v[180:183], v[56:59]
	v_mfma_f32_16x16x32_bf16 v[64:67], v[156:159], v[194:197], v[64:67]
	v_mfma_f32_16x16x32_bf16 v[64:67], v[160:163], v[198:201], v[64:67]
	s_setprio 2
	s_barrier
	v_mfma_f32_16x16x32_bf16 v[60:63], v[152:155], v[198:201], v[60:63]
	v_mfma_f32_16x16x32_bf16 v[60:63], v[148:151], v[194:197], v[60:63]
	s_setprio 0
	s_add_i32 s38, s71, s54
	s_mov_b32 m0, s38
	ds_read_b128 v[164:167], v231 offset:16384
	ds_read_b128 v[168:171], v231 offset:17408
	ds_read_b128 v[172:175], v231 offset:18432
	ds_read_b128 v[176:179], v231 offset:19456
	ds_read_b128 v[180:183], v231 offset:20480
	ds_read_b128 v[184:187], v231 offset:21504
	ds_read_b128 v[194:197], v231 offset:22528
	ds_read_b128 v[198:201], v231 offset:23552
	global_load_lds_dwordx4 v192, s[16:17]
	s_add_i32 m0, s38, 0x2000
	s_add_u32 s42, s16, 0x160000
	s_addc_u32 s43, s17, 0
	s_add_i32 s38, s72, s54
	global_load_lds_dwordx4 v190, s[16:17]
	s_mov_b32 m0, s38
	v_mov_b32_e32 v193, v3
	global_load_lds_dwordx4 v192, s[42:43]
	s_add_i32 m0, s38, 0x2000
	v_mov_b32_e32 v191, v3
	global_load_lds_dwordx4 v190, s[42:43]
	s_mov_b32 m0, s55
	s_nop 0
	global_load_lds_dwordx4 v2, s[26:27]
	s_mov_b32 m0, s56
	s_nop 0
	global_load_lds_dwordx4 v188, s[26:27]
	s_waitcnt vmcnt(8)
	s_waitcnt lgkmcnt(0)
	s_add_u32 s88, s16, s4
	s_addc_u32 s89, s17, s5
	s_add_u32 s90, s26, s4
	s_addc_u32 s91, s27, s5
	s_barrier
	s_setprio 1
	s_waitcnt lgkmcnt(0)
	v_mfma_f32_16x16x32_bf16 v[68:71], v[132:135], v[164:167], v[68:71]
	v_mfma_f32_16x16x32_bf16 v[68:71], v[136:139], v[168:171], v[68:71]
	v_mfma_f32_16x16x32_bf16 v[72:75], v[144:147], v[168:171], v[72:75]
	v_mfma_f32_16x16x32_bf16 v[72:75], v[140:143], v[164:167], v[72:75]
	v_mfma_f32_16x16x32_bf16 v[80:83], v[140:143], v[172:175], v[80:83]
	v_mfma_f32_16x16x32_bf16 v[80:83], v[144:147], v[176:179], v[80:83]
	v_mfma_f32_16x16x32_bf16 v[76:79], v[136:139], v[176:179], v[76:79]
	v_mfma_f32_16x16x32_bf16 v[76:79], v[132:135], v[172:175], v[76:79]
	v_mfma_f32_16x16x32_bf16 v[84:87], v[132:135], v[180:183], v[84:87]
	v_mfma_f32_16x16x32_bf16 v[84:87], v[136:139], v[184:187], v[84:87]
	v_mfma_f32_16x16x32_bf16 v[88:91], v[144:147], v[184:187], v[88:91]
	v_mfma_f32_16x16x32_bf16 v[88:91], v[140:143], v[180:183], v[88:91]
	v_mfma_f32_16x16x32_bf16 v[96:99], v[140:143], v[194:197], v[96:99]
	v_mfma_f32_16x16x32_bf16 v[96:99], v[144:147], v[198:201], v[96:99]
	v_mfma_f32_16x16x32_bf16 v[92:95], v[136:139], v[198:201], v[92:95]
	v_mfma_f32_16x16x32_bf16 v[92:95], v[132:135], v[194:197], v[92:95]
	s_setprio 0
	s_setprio 1
	v_mfma_f32_16x16x32_bf16 v[100:103], v[148:151], v[164:167], v[100:103]
	v_mfma_f32_16x16x32_bf16 v[100:103], v[152:155], v[168:171], v[100:103]
	v_mfma_f32_16x16x32_bf16 v[104:107], v[160:163], v[168:171], v[104:107]
	v_mfma_f32_16x16x32_bf16 v[104:107], v[156:159], v[164:167], v[104:107]
	v_mfma_f32_16x16x32_bf16 v[112:115], v[156:159], v[172:175], v[112:115]
	v_mfma_f32_16x16x32_bf16 v[112:115], v[160:163], v[176:179], v[112:115]
	v_mfma_f32_16x16x32_bf16 v[108:111], v[152:155], v[176:179], v[108:111]
	v_mfma_f32_16x16x32_bf16 v[108:111], v[148:151], v[172:175], v[108:111]
	v_mfma_f32_16x16x32_bf16 v[116:119], v[148:151], v[180:183], v[116:119]
	v_mfma_f32_16x16x32_bf16 v[116:119], v[152:155], v[184:187], v[116:119]
	v_mfma_f32_16x16x32_bf16 v[120:123], v[160:163], v[184:187], v[120:123]
	v_mfma_f32_16x16x32_bf16 v[120:123], v[156:159], v[180:183], v[120:123]
	v_mfma_f32_16x16x32_bf16 v[128:131], v[156:159], v[194:197], v[128:131]
	v_mfma_f32_16x16x32_bf16 v[128:131], v[160:163], v[198:201], v[128:131]
	s_setprio 2
	s_barrier
	v_mfma_f32_16x16x32_bf16 v[124:127], v[152:155], v[198:201], v[124:127]
	v_mfma_f32_16x16x32_bf16 v[124:127], v[148:151], v[194:197], v[124:127]
	s_setprio 0
	s_add_i32 s38, 0, 0x18000
	s_add_i32 s42, 0, 0x1c000
	ds_read_b128 v[132:135], v240 offset:32768
	ds_read_b128 v[136:139], v240 offset:33792
	ds_read_b128 v[140:143], v240 offset:34816
	ds_read_b128 v[144:147], v240 offset:35840
	ds_read_b128 v[148:151], v240 offset:49152
	ds_read_b128 v[152:155], v240 offset:50176
	ds_read_b128 v[156:159], v240 offset:51200
	ds_read_b128 v[160:163], v240 offset:52224
	s_add_u32 s26, s26, 0x160000
	s_addc_u32 s27, s27, 0
	s_mov_b32 m0, s57
	ds_read_b128 v[164:167], v231 offset:32768
	ds_read_b128 v[168:171], v231 offset:33792
	ds_read_b128 v[172:175], v231 offset:34816
	ds_read_b128 v[176:179], v231 offset:35840
	ds_read_b128 v[180:183], v231 offset:36864
	ds_read_b128 v[184:187], v231 offset:37888
	ds_read_b128 v[194:197], v231 offset:38912
	ds_read_b128 v[198:201], v231 offset:39936
	global_load_lds_dwordx4 v2, s[26:27]
	s_mov_b32 m0, s58
	s_nop 0
	global_load_lds_dwordx4 v188, s[26:27]
	s_waitcnt vmcnt(8)
	s_waitcnt lgkmcnt(0)
	s_barrier
	s_setprio 1
	s_waitcnt lgkmcnt(0)
	v_mfma_f32_16x16x32_bf16 v[4:7], v[132:135], v[164:167], v[4:7]
	v_mfma_f32_16x16x32_bf16 v[4:7], v[136:139], v[168:171], v[4:7]
	v_mfma_f32_16x16x32_bf16 v[8:11], v[144:147], v[168:171], v[8:11]
	v_mfma_f32_16x16x32_bf16 v[8:11], v[140:143], v[164:167], v[8:11]
	v_mfma_f32_16x16x32_bf16 v[16:19], v[140:143], v[172:175], v[16:19]
	v_mfma_f32_16x16x32_bf16 v[16:19], v[144:147], v[176:179], v[16:19]
	v_mfma_f32_16x16x32_bf16 v[12:15], v[136:139], v[176:179], v[12:15]
	v_mfma_f32_16x16x32_bf16 v[12:15], v[132:135], v[172:175], v[12:15]
	v_mfma_f32_16x16x32_bf16 v[20:23], v[132:135], v[180:183], v[20:23]
	v_mfma_f32_16x16x32_bf16 v[20:23], v[136:139], v[184:187], v[20:23]
	v_mfma_f32_16x16x32_bf16 v[24:27], v[144:147], v[184:187], v[24:27]
	v_mfma_f32_16x16x32_bf16 v[24:27], v[140:143], v[180:183], v[24:27]
	v_mfma_f32_16x16x32_bf16 v[32:35], v[140:143], v[194:197], v[32:35]
	v_mfma_f32_16x16x32_bf16 v[32:35], v[144:147], v[198:201], v[32:35]
	v_mfma_f32_16x16x32_bf16 v[28:31], v[136:139], v[198:201], v[28:31]
	v_mfma_f32_16x16x32_bf16 v[28:31], v[132:135], v[194:197], v[28:31]
	s_setprio 0
	s_setprio 1
	v_mfma_f32_16x16x32_bf16 v[36:39], v[148:151], v[164:167], v[36:39]
	v_mfma_f32_16x16x32_bf16 v[36:39], v[152:155], v[168:171], v[36:39]
	v_mfma_f32_16x16x32_bf16 v[40:43], v[160:163], v[168:171], v[40:43]
	v_mfma_f32_16x16x32_bf16 v[40:43], v[156:159], v[164:167], v[40:43]
	v_mfma_f32_16x16x32_bf16 v[48:51], v[156:159], v[172:175], v[48:51]
	v_mfma_f32_16x16x32_bf16 v[48:51], v[160:163], v[176:179], v[48:51]
	v_mfma_f32_16x16x32_bf16 v[44:47], v[152:155], v[176:179], v[44:47]
	v_mfma_f32_16x16x32_bf16 v[44:47], v[148:151], v[172:175], v[44:47]
	v_mfma_f32_16x16x32_bf16 v[52:55], v[148:151], v[180:183], v[52:55]
	v_mfma_f32_16x16x32_bf16 v[52:55], v[152:155], v[184:187], v[52:55]
	v_mfma_f32_16x16x32_bf16 v[56:59], v[160:163], v[184:187], v[56:59]
	v_mfma_f32_16x16x32_bf16 v[56:59], v[156:159], v[180:183], v[56:59]
	v_mfma_f32_16x16x32_bf16 v[64:67], v[156:159], v[194:197], v[64:67]
	v_mfma_f32_16x16x32_bf16 v[64:67], v[160:163], v[198:201], v[64:67]
	s_setprio 2
	s_barrier
	v_mfma_f32_16x16x32_bf16 v[60:63], v[152:155], v[198:201], v[60:63]
	v_mfma_f32_16x16x32_bf16 v[60:63], v[148:151], v[194:197], v[60:63]
	s_setprio 0
	s_add_i32 s26, s38, s54
	s_mov_b32 m0, s26
	ds_read_b128 v[164:167], v231 offset:49152
	ds_read_b128 v[168:171], v231 offset:50176
	ds_read_b128 v[172:175], v231 offset:51200
	ds_read_b128 v[176:179], v231 offset:52224
	ds_read_b128 v[180:183], v231 offset:53248
	ds_read_b128 v[184:187], v231 offset:54272
	ds_read_b128 v[194:197], v231 offset:55296
	ds_read_b128 v[198:201], v231 offset:56320
	global_load_lds_dwordx4 v192, s[88:89]
	s_add_i32 m0, s26, 0x2000
	s_add_u32 s16, s16, 0x15ff80
	s_addc_u32 s17, s17, 0
	s_add_i32 s26, s42, s54
	global_load_lds_dwordx4 v190, s[88:89]
	s_mov_b32 m0, s26
	s_nop 0
	global_load_lds_dwordx4 v192, s[16:17]
	s_add_i32 m0, s26, 0x2000
	s_nop 0
	global_load_lds_dwordx4 v190, s[16:17]
	s_mov_b32 m0, s62
	s_nop 0
	global_load_lds_dwordx4 v2, s[90:91]
	s_mov_b32 m0, s63
	s_nop 0
	global_load_lds_dwordx4 v188, s[90:91]
	s_waitcnt vmcnt(8)
	s_waitcnt lgkmcnt(0)
	s_barrier
	s_setprio 1
	s_waitcnt lgkmcnt(0)
	v_mfma_f32_16x16x32_bf16 v[68:71], v[132:135], v[164:167], v[68:71]
	v_mfma_f32_16x16x32_bf16 v[68:71], v[136:139], v[168:171], v[68:71]
	v_mfma_f32_16x16x32_bf16 v[72:75], v[144:147], v[168:171], v[72:75]
	v_mfma_f32_16x16x32_bf16 v[72:75], v[140:143], v[164:167], v[72:75]
	v_mfma_f32_16x16x32_bf16 v[80:83], v[140:143], v[172:175], v[80:83]
	v_mfma_f32_16x16x32_bf16 v[80:83], v[144:147], v[176:179], v[80:83]
	v_mfma_f32_16x16x32_bf16 v[76:79], v[136:139], v[176:179], v[76:79]
	v_mfma_f32_16x16x32_bf16 v[76:79], v[132:135], v[172:175], v[76:79]
	v_mfma_f32_16x16x32_bf16 v[84:87], v[132:135], v[180:183], v[84:87]
	v_mfma_f32_16x16x32_bf16 v[84:87], v[136:139], v[184:187], v[84:87]
	v_mfma_f32_16x16x32_bf16 v[88:91], v[144:147], v[184:187], v[88:91]
	v_mfma_f32_16x16x32_bf16 v[88:91], v[140:143], v[180:183], v[88:91]
	v_mfma_f32_16x16x32_bf16 v[96:99], v[140:143], v[194:197], v[96:99]
	v_mfma_f32_16x16x32_bf16 v[96:99], v[144:147], v[198:201], v[96:99]
	v_mfma_f32_16x16x32_bf16 v[92:95], v[136:139], v[198:201], v[92:95]
	v_mfma_f32_16x16x32_bf16 v[92:95], v[132:135], v[194:197], v[92:95]
	s_setprio 0
	s_setprio 1
	v_mfma_f32_16x16x32_bf16 v[100:103], v[148:151], v[164:167], v[100:103]
	v_mfma_f32_16x16x32_bf16 v[100:103], v[152:155], v[168:171], v[100:103]
	v_mfma_f32_16x16x32_bf16 v[104:107], v[160:163], v[168:171], v[104:107]
	v_mfma_f32_16x16x32_bf16 v[104:107], v[156:159], v[164:167], v[104:107]
	v_mfma_f32_16x16x32_bf16 v[112:115], v[156:159], v[172:175], v[112:115]
	v_mfma_f32_16x16x32_bf16 v[112:115], v[160:163], v[176:179], v[112:115]
	v_mfma_f32_16x16x32_bf16 v[108:111], v[152:155], v[176:179], v[108:111]
	v_mfma_f32_16x16x32_bf16 v[108:111], v[148:151], v[172:175], v[108:111]
	v_mfma_f32_16x16x32_bf16 v[116:119], v[148:151], v[180:183], v[116:119]
	v_mfma_f32_16x16x32_bf16 v[116:119], v[152:155], v[184:187], v[116:119]
	v_mfma_f32_16x16x32_bf16 v[120:123], v[160:163], v[184:187], v[120:123]
	v_mfma_f32_16x16x32_bf16 v[120:123], v[156:159], v[180:183], v[120:123]
	v_mfma_f32_16x16x32_bf16 v[128:131], v[156:159], v[194:197], v[128:131]
	v_mfma_f32_16x16x32_bf16 v[128:131], v[160:163], v[198:201], v[128:131]
	s_setprio 2
	s_barrier
	v_mfma_f32_16x16x32_bf16 v[124:127], v[152:155], v[198:201], v[124:127]
	v_mfma_f32_16x16x32_bf16 v[124:127], v[148:151], v[194:197], v[124:127]
	s_setprio 0
	s_cmpk_gt_u32 s28, 0x55
	s_cbranch_scc1 .LBB0_651
	s_mov_b32 s28, s29
	s_branch .LBB0_645
